# grid barrier: last-arriving XCD leader releases all XCDs' workgroups directly (bumps every XGEN word after TOPGEN); other leaders no longer forward the release
# baseline (speedup 1.0000x reference)
; __device__ __forceinline__ unsigned xb_ld(unsigned* p)              { return __hip_atomic_load(p, __ATOMIC_RELAXED, __HIP_MEMORY_SCOPE_AGENT); }
; __device__ __forceinline__ unsigned xb_add(unsigned* p, unsigned v) { return __hip_atomic_fetch_add(p, v, __ATOMIC_RELAXED, __HIP_MEMORY_SCOPE_AGENT); }
; #define XB_SPIN(cond, bar) do { unsigned _sp = 0; while (cond) { __builtin_amdgcn_s_sleep(1); \
;     if ((++_sp & 255u) == 0u) { if (xb_ld(&(bar)[XB_TMO])) break; if (_sp > XB_SPIN_CAP) { atomicAdd(&(bar)[XB_TMO], 1u); break; } } } } while (0)
; __device__ __forceinline__ void xcd_barrier(const XcdBarrier& b) {
;     ...
;         const unsigned old = xb_add(&bar[XB_XSUB(b.x)], 1u);
;         const unsigned gen = old / nloc;
;         if (old + 1u == (gen + 1u) * nloc) {
;             __builtin_amdgcn_fence(__ATOMIC_RELEASE, "agent");
;             asm volatile("s_waitcnt vmcnt(0)" ::: "memory");
;             const unsigned og = xb_add(&bar[XB_TOP], 1u);
;             const unsigned tg = og / nx;
;             if (og + 1u == (tg + 1u) * nx) xb_add(&bar[XB_TOPGEN], 1u);
;             else XB_SPIN(xb_ld(&bar[XB_TOPGEN]) == tg, bar);
;             __builtin_amdgcn_fence(__ATOMIC_ACQUIRE, "agent");
;             xb_add(&bar[XB_XGEN(b.x)], 1u);
;             asm volatile("s_waitcnt vmcnt(0)" ::: "memory");
;         } else {
;             XB_SPIN(xb_ld(&bar[XB_XGEN(b.x)]) == gen, bar);
;             __builtin_amdgcn_fence(__ATOMIC_ACQUIRE, "agent");
;             asm volatile("s_waitcnt vmcnt(0)" ::: "memory");
;         }
.LBB0_120:
	s_or_b64 exec, exec, s[6:7]
	s_and_saveexec_b64 s[6:7], s[10:11]
	s_cbranch_execz .LBB0_122
	v_mov_b32_e32 v2, 1
	global_atomic_add v[0:1], v2, off
	v_mov_b32_e32 v3, 0xde400
	global_atomic_add v3, v2, s[50:51] offset:0
	global_atomic_add v3, v2, s[50:51] offset:256
	global_atomic_add v3, v2, s[50:51] offset:512
	global_atomic_add v3, v2, s[50:51] offset:768
	global_atomic_add v3, v2, s[50:51] offset:1024
	global_atomic_add v3, v2, s[50:51] offset:1280
	global_atomic_add v3, v2, s[50:51] offset:1536
	global_atomic_add v3, v2, s[50:51] offset:1792
.LBB0_122:
	s_or_b64 exec, exec, s[6:7]
	s_mov_b64 s[6:7], exec
	v_mbcnt_lo_u32_b32 v0, s6, 0
	v_mbcnt_hi_u32_b32 v0, s7, v0
	v_cmp_eq_u32_e32 vcc, 0, v0
	s_waitcnt vmcnt(0)
	buffer_inv sc1
	s_and_saveexec_b64 s[8:9], vcc
	s_cbranch_execz .LBB0_124
	s_bcnt1_i32_b64 s6, s[6:7]
	v_mov_b32_e32 v0, 0x2000
	v_mov_b32_e32 v1, s6
.LBB0_124:
	s_or_b64 exec, exec, s[8:9]
	s_waitcnt vmcnt(0)

; __device__ __forceinline__ unsigned xb_ld(unsigned* p)              { return __hip_atomic_load(p, __ATOMIC_RELAXED, __HIP_MEMORY_SCOPE_AGENT); }
; __device__ __forceinline__ unsigned xb_add(unsigned* p, unsigned v) { return __hip_atomic_fetch_add(p, v, __ATOMIC_RELAXED, __HIP_MEMORY_SCOPE_AGENT); }
; #define XB_SPIN(cond, bar) do { unsigned _sp = 0; while (cond) { __builtin_amdgcn_s_sleep(1); \
;     if ((++_sp & 255u) == 0u) { if (xb_ld(&(bar)[XB_TMO])) break; if (_sp > XB_SPIN_CAP) { atomicAdd(&(bar)[XB_TMO], 1u); break; } } } } while (0)
; __device__ __forceinline__ void xcd_barrier(const XcdBarrier& b) {
;     ...
;             __builtin_amdgcn_fence(__ATOMIC_ACQUIRE, "agent");
;             xb_add(&bar[XB_XGEN(b.x)], 1u);
;             asm volatile("s_waitcnt vmcnt(0)" ::: "memory");
;         } else {
;             XB_SPIN(xb_ld(&bar[XB_XGEN(b.x)]) == gen, bar);
;             __builtin_amdgcn_fence(__ATOMIC_ACQUIRE, "agent");
;             asm volatile("s_waitcnt vmcnt(0)" ::: "memory");
.LBB0_177:
	s_or_b64 exec, exec, s[6:7]
	s_mov_b64 s[6:7], exec
	v_mbcnt_lo_u32_b32 v0, s6, 0
	v_mbcnt_hi_u32_b32 v0, s7, v0
	v_cmp_eq_u32_e32 vcc, 0, v0
	s_waitcnt vmcnt(0)
	buffer_inv sc1
	s_and_saveexec_b64 s[8:9], vcc
	s_cbranch_execz .LBB0_179
	s_bcnt1_i32_b64 s6, s[6:7]
	v_mov_b32_e32 v0, 0x2000
	v_mov_b32_e32 v1, s6
.LBB0_179:
	s_or_b64 exec, exec, s[8:9]
	s_waitcnt vmcnt(0)

; __device__ __forceinline__ unsigned xb_ld(unsigned* p)              { return __hip_atomic_load(p, __ATOMIC_RELAXED, __HIP_MEMORY_SCOPE_AGENT); }
; __device__ __forceinline__ unsigned xb_add(unsigned* p, unsigned v) { return __hip_atomic_fetch_add(p, v, __ATOMIC_RELAXED, __HIP_MEMORY_SCOPE_AGENT); }
; #define XB_SPIN(cond, bar) do { unsigned _sp = 0; while (cond) { __builtin_amdgcn_s_sleep(1); \
;     if ((++_sp & 255u) == 0u) { if (xb_ld(&(bar)[XB_TMO])) break; if (_sp > XB_SPIN_CAP) { atomicAdd(&(bar)[XB_TMO], 1u); break; } } } } while (0)
; __device__ __forceinline__ void xcd_barrier(const XcdBarrier& b) {
;     ...
;             const unsigned og = xb_add(&bar[XB_TOP], 1u);
;             const unsigned tg = og / nx;
;             if (og + 1u == (tg + 1u) * nx) xb_add(&bar[XB_TOPGEN], 1u);
;             else XB_SPIN(xb_ld(&bar[XB_TOPGEN]) == tg, bar);
;             __builtin_amdgcn_fence(__ATOMIC_ACQUIRE, "agent");
;             xb_add(&bar[XB_XGEN(b.x)], 1u);
;             asm volatile("s_waitcnt vmcnt(0)" ::: "memory");
;         } else {
;             XB_SPIN(xb_ld(&bar[XB_XGEN(b.x)]) == gen, bar);
;             __builtin_amdgcn_fence(__ATOMIC_ACQUIRE, "agent");
;             asm volatile("s_waitcnt vmcnt(0)" ::: "memory");
.LBB0_250:
	s_or_b64 exec, exec, s[6:7]
	s_and_saveexec_b64 s[6:7], s[8:9]
	s_cbranch_execz .LBB0_252
	global_atomic_add v[0:1], v156, off
	v_readlane_b32 vcc_lo, v253, 63
	v_readlane_b32 vcc_hi, v254, 0
	s_nop 4
	global_atomic_add v97, v156, vcc offset:-4096
	global_atomic_add v97, v156, vcc offset:-3840
	global_atomic_add v97, v156, vcc offset:-3584
	global_atomic_add v97, v156, vcc offset:-3328
	global_atomic_add v97, v156, vcc offset:-3072
	global_atomic_add v97, v156, vcc offset:-2816
	global_atomic_add v97, v156, vcc offset:-2560
	global_atomic_add v97, v156, vcc offset:-2304
.LBB0_252:
	s_or_b64 exec, exec, s[6:7]
	s_mov_b64 s[6:7], exec
	v_mbcnt_lo_u32_b32 v0, s6, 0
	v_mbcnt_hi_u32_b32 v0, s7, v0
	v_cmp_eq_u32_e32 vcc, 0, v0
	s_waitcnt vmcnt(0)
	buffer_inv sc1
	s_and_saveexec_b64 s[8:9], vcc
	s_cbranch_execz .LBB0_254
	s_bcnt1_i32_b64 s6, s[6:7]
	v_mov_b32_e32 v0, s6
.LBB0_254:
	s_or_b64 exec, exec, s[8:9]
	s_waitcnt vmcnt(0)

; __device__ __forceinline__ unsigned xb_ld(unsigned* p)              { return __hip_atomic_load(p, __ATOMIC_RELAXED, __HIP_MEMORY_SCOPE_AGENT); }
; __device__ __forceinline__ unsigned xb_add(unsigned* p, unsigned v) { return __hip_atomic_fetch_add(p, v, __ATOMIC_RELAXED, __HIP_MEMORY_SCOPE_AGENT); }
; #define XB_SPIN(cond, bar) do { unsigned _sp = 0; while (cond) { __builtin_amdgcn_s_sleep(1); \
;     if ((++_sp & 255u) == 0u) { if (xb_ld(&(bar)[XB_TMO])) break; if (_sp > XB_SPIN_CAP) { atomicAdd(&(bar)[XB_TMO], 1u); break; } } } } while (0)
; __device__ __forceinline__ void xcd_barrier(const XcdBarrier& b) {
;     ...
;             __builtin_amdgcn_fence(__ATOMIC_ACQUIRE, "agent");
;             xb_add(&bar[XB_XGEN(b.x)], 1u);
;             asm volatile("s_waitcnt vmcnt(0)" ::: "memory");
;         } else {
;             XB_SPIN(xb_ld(&bar[XB_XGEN(b.x)]) == gen, bar);
;             __builtin_amdgcn_fence(__ATOMIC_ACQUIRE, "agent");
;             asm volatile("s_waitcnt vmcnt(0)" ::: "memory");
.LBB0_352:
	s_or_b64 exec, exec, s[6:7]
	s_mov_b64 s[6:7], exec
	v_mbcnt_lo_u32_b32 v0, s6, 0
	v_mbcnt_hi_u32_b32 v0, s7, v0
	v_cmp_eq_u32_e32 vcc, 0, v0
	s_waitcnt vmcnt(0)
	buffer_inv sc1
	s_and_saveexec_b64 s[8:9], vcc
	s_cbranch_execz .LBB0_354
	s_bcnt1_i32_b64 s6, s[6:7]
	v_mov_b32_e32 v0, s6
.LBB0_354:
	s_or_b64 exec, exec, s[8:9]
	s_waitcnt vmcnt(0)

; __device__ __forceinline__ unsigned xb_ld(unsigned* p)              { return __hip_atomic_load(p, __ATOMIC_RELAXED, __HIP_MEMORY_SCOPE_AGENT); }
; __device__ __forceinline__ unsigned xb_add(unsigned* p, unsigned v) { return __hip_atomic_fetch_add(p, v, __ATOMIC_RELAXED, __HIP_MEMORY_SCOPE_AGENT); }
; #define XB_SPIN(cond, bar) do { unsigned _sp = 0; while (cond) { __builtin_amdgcn_s_sleep(1); \
;     if ((++_sp & 255u) == 0u) { if (xb_ld(&(bar)[XB_TMO])) break; if (_sp > XB_SPIN_CAP) { atomicAdd(&(bar)[XB_TMO], 1u); break; } } } } while (0)
; __device__ __forceinline__ void xcd_barrier(const XcdBarrier& b) {
;     ...
;             __builtin_amdgcn_fence(__ATOMIC_ACQUIRE, "agent");
;             xb_add(&bar[XB_XGEN(b.x)], 1u);
;             asm volatile("s_waitcnt vmcnt(0)" ::: "memory");
;         } else {
;             XB_SPIN(xb_ld(&bar[XB_XGEN(b.x)]) == gen, bar);
;             __builtin_amdgcn_fence(__ATOMIC_ACQUIRE, "agent");
;             asm volatile("s_waitcnt vmcnt(0)" ::: "memory");
.LBB0_503:
	s_or_b64 exec, exec, s[6:7]
	s_mov_b64 s[6:7], exec
	v_mbcnt_lo_u32_b32 v0, s6, 0
	v_mbcnt_hi_u32_b32 v0, s7, v0
	v_cmp_eq_u32_e32 vcc, 0, v0
	s_waitcnt vmcnt(0)
	buffer_inv sc1
	s_and_saveexec_b64 s[8:9], vcc
	s_cbranch_execz .LBB0_505
	s_bcnt1_i32_b64 s6, s[6:7]
	v_mov_b32_e32 v0, s6
.LBB0_505:
	s_or_b64 exec, exec, s[8:9]
	s_waitcnt vmcnt(0)

; __device__ __forceinline__ unsigned xb_ld(unsigned* p)              { return __hip_atomic_load(p, __ATOMIC_RELAXED, __HIP_MEMORY_SCOPE_AGENT); }
; __device__ __forceinline__ unsigned xb_add(unsigned* p, unsigned v) { return __hip_atomic_fetch_add(p, v, __ATOMIC_RELAXED, __HIP_MEMORY_SCOPE_AGENT); }
; #define XB_SPIN(cond, bar) do { unsigned _sp = 0; while (cond) { __builtin_amdgcn_s_sleep(1); \
;     if ((++_sp & 255u) == 0u) { if (xb_ld(&(bar)[XB_TMO])) break; if (_sp > XB_SPIN_CAP) { atomicAdd(&(bar)[XB_TMO], 1u); break; } } } } while (0)
; __device__ __forceinline__ void xcd_barrier(const XcdBarrier& b) {
;     ...
;             __builtin_amdgcn_fence(__ATOMIC_ACQUIRE, "agent");
;             xb_add(&bar[XB_XGEN(b.x)], 1u);
;             asm volatile("s_waitcnt vmcnt(0)" ::: "memory");
;         } else {
;             XB_SPIN(xb_ld(&bar[XB_XGEN(b.x)]) == gen, bar);
;             __builtin_amdgcn_fence(__ATOMIC_ACQUIRE, "agent");
;             asm volatile("s_waitcnt vmcnt(0)" ::: "memory");
.LBB0_649:
	s_or_b64 exec, exec, s[6:7]
	s_mov_b64 s[6:7], exec
	v_mbcnt_lo_u32_b32 v0, s6, 0
	v_mbcnt_hi_u32_b32 v0, s7, v0
	v_cmp_eq_u32_e32 vcc, 0, v0
	s_waitcnt vmcnt(0)
	buffer_inv sc1
	s_and_saveexec_b64 s[8:9], vcc
	s_cbranch_execz .LBB0_651
	s_bcnt1_i32_b64 s6, s[6:7]
	v_mov_b32_e32 v0, s6
.LBB0_651:
	s_or_b64 exec, exec, s[8:9]
	s_waitcnt vmcnt(0)

; __device__ __forceinline__ unsigned xb_ld(unsigned* p)              { return __hip_atomic_load(p, __ATOMIC_RELAXED, __HIP_MEMORY_SCOPE_AGENT); }
; __device__ __forceinline__ unsigned xb_add(unsigned* p, unsigned v) { return __hip_atomic_fetch_add(p, v, __ATOMIC_RELAXED, __HIP_MEMORY_SCOPE_AGENT); }
; #define XB_SPIN(cond, bar) do { unsigned _sp = 0; while (cond) { __builtin_amdgcn_s_sleep(1); \
;     if ((++_sp & 255u) == 0u) { if (xb_ld(&(bar)[XB_TMO])) break; if (_sp > XB_SPIN_CAP) { atomicAdd(&(bar)[XB_TMO], 1u); break; } } } } while (0)
; __device__ __forceinline__ void xcd_barrier(const XcdBarrier& b) {
;     ...
;             __builtin_amdgcn_fence(__ATOMIC_ACQUIRE, "agent");
;             xb_add(&bar[XB_XGEN(b.x)], 1u);
;             asm volatile("s_waitcnt vmcnt(0)" ::: "memory");
;         } else {
;             XB_SPIN(xb_ld(&bar[XB_XGEN(b.x)]) == gen, bar);
;             __builtin_amdgcn_fence(__ATOMIC_ACQUIRE, "agent");
;             asm volatile("s_waitcnt vmcnt(0)" ::: "memory");
.LBB0_716:
	s_or_b64 exec, exec, s[6:7]
	s_mov_b64 s[6:7], exec
	v_mbcnt_lo_u32_b32 v0, s6, 0
	v_mbcnt_hi_u32_b32 v0, s7, v0
	v_cmp_eq_u32_e32 vcc, 0, v0
	s_waitcnt vmcnt(0)
	buffer_inv sc1
	s_and_saveexec_b64 s[8:9], vcc
	s_cbranch_execz .LBB0_718
	s_bcnt1_i32_b64 s6, s[6:7]
	v_mov_b32_e32 v0, s6
.LBB0_718:
	s_or_b64 exec, exec, s[8:9]
	s_waitcnt vmcnt(0)

; __device__ __forceinline__ unsigned xb_ld(unsigned* p)              { return __hip_atomic_load(p, __ATOMIC_RELAXED, __HIP_MEMORY_SCOPE_AGENT); }
; __device__ __forceinline__ unsigned xb_add(unsigned* p, unsigned v) { return __hip_atomic_fetch_add(p, v, __ATOMIC_RELAXED, __HIP_MEMORY_SCOPE_AGENT); }
; #define XB_SPIN(cond, bar) do { unsigned _sp = 0; while (cond) { __builtin_amdgcn_s_sleep(1); \
;     if ((++_sp & 255u) == 0u) { if (xb_ld(&(bar)[XB_TMO])) break; if (_sp > XB_SPIN_CAP) { atomicAdd(&(bar)[XB_TMO], 1u); break; } } } } while (0)
; __device__ __forceinline__ void xcd_barrier(const XcdBarrier& b) {
;     ...
;             __builtin_amdgcn_fence(__ATOMIC_ACQUIRE, "agent");
;             xb_add(&bar[XB_XGEN(b.x)], 1u);
;             asm volatile("s_waitcnt vmcnt(0)" ::: "memory");
;         } else {
;             XB_SPIN(xb_ld(&bar[XB_XGEN(b.x)]) == gen, bar);
;             __builtin_amdgcn_fence(__ATOMIC_ACQUIRE, "agent");
;             asm volatile("s_waitcnt vmcnt(0)" ::: "memory");
.LBB0_874:
	s_or_b64 exec, exec, s[6:7]
	s_mov_b64 s[6:7], exec
	v_mbcnt_lo_u32_b32 v0, s6, 0
	v_mbcnt_hi_u32_b32 v0, s7, v0
	v_cmp_eq_u32_e32 vcc, 0, v0
	s_waitcnt vmcnt(0)
	buffer_inv sc1
	s_and_saveexec_b64 s[8:9], vcc
	s_cbranch_execz .LBB0_876
	s_bcnt1_i32_b64 s6, s[6:7]
	v_mov_b32_e32 v0, s6
.LBB0_876:
	s_or_b64 exec, exec, s[8:9]
	s_waitcnt vmcnt(0)

; __device__ __forceinline__ unsigned xb_ld(unsigned* p)              { return __hip_atomic_load(p, __ATOMIC_RELAXED, __HIP_MEMORY_SCOPE_AGENT); }
; __device__ __forceinline__ unsigned xb_add(unsigned* p, unsigned v) { return __hip_atomic_fetch_add(p, v, __ATOMIC_RELAXED, __HIP_MEMORY_SCOPE_AGENT); }
; #define XB_SPIN(cond, bar) do { unsigned _sp = 0; while (cond) { __builtin_amdgcn_s_sleep(1); \
;     if ((++_sp & 255u) == 0u) { if (xb_ld(&(bar)[XB_TMO])) break; if (_sp > XB_SPIN_CAP) { atomicAdd(&(bar)[XB_TMO], 1u); break; } } } } while (0)
; __device__ __forceinline__ void xcd_barrier(const XcdBarrier& b) {
;     ...
;             const unsigned og = xb_add(&bar[XB_TOP], 1u);
;             const unsigned tg = og / nx;
;             if (og + 1u == (tg + 1u) * nx) xb_add(&bar[XB_TOPGEN], 1u);
;             else XB_SPIN(xb_ld(&bar[XB_TOPGEN]) == tg, bar);
;             __builtin_amdgcn_fence(__ATOMIC_ACQUIRE, "agent");
;             xb_add(&bar[XB_XGEN(b.x)], 1u);
;             asm volatile("s_waitcnt vmcnt(0)" ::: "memory");
;         } else {
;             XB_SPIN(xb_ld(&bar[XB_XGEN(b.x)]) == gen, bar);
;             __builtin_amdgcn_fence(__ATOMIC_ACQUIRE, "agent");
;             asm volatile("s_waitcnt vmcnt(0)" ::: "memory");
.LBB0_947:
	s_or_b64 exec, exec, s[8:9]
	s_and_saveexec_b64 s[8:9], s[10:11]
	s_cbranch_execz .LBB0_949
	global_atomic_add v[0:1], v156, off
	v_readlane_b32 vcc_lo, v253, 63
	v_readlane_b32 vcc_hi, v254, 0
	s_nop 4
	global_atomic_add v97, v156, vcc offset:-4096
	global_atomic_add v97, v156, vcc offset:-3840
	global_atomic_add v97, v156, vcc offset:-3584
	global_atomic_add v97, v156, vcc offset:-3328
	global_atomic_add v97, v156, vcc offset:-3072
	global_atomic_add v97, v156, vcc offset:-2816
	global_atomic_add v97, v156, vcc offset:-2560
	global_atomic_add v97, v156, vcc offset:-2304
.LBB0_949:
	s_or_b64 exec, exec, s[8:9]
	s_mov_b64 s[8:9], exec
	v_mbcnt_lo_u32_b32 v0, s8, 0
	v_mbcnt_hi_u32_b32 v0, s9, v0
	v_cmp_eq_u32_e32 vcc, 0, v0
	s_waitcnt vmcnt(0)
	buffer_inv sc1
	s_and_saveexec_b64 s[10:11], vcc
	s_cbranch_execz .LBB0_951
	s_bcnt1_i32_b64 s8, s[8:9]
	v_mov_b32_e32 v0, s8
.LBB0_951:
	s_or_b64 exec, exec, s[10:11]
	s_waitcnt vmcnt(0)

; __device__ __forceinline__ unsigned xb_ld(unsigned* p)              { return __hip_atomic_load(p, __ATOMIC_RELAXED, __HIP_MEMORY_SCOPE_AGENT); }
; __device__ __forceinline__ unsigned xb_add(unsigned* p, unsigned v) { return __hip_atomic_fetch_add(p, v, __ATOMIC_RELAXED, __HIP_MEMORY_SCOPE_AGENT); }
; #define XB_SPIN(cond, bar) do { unsigned _sp = 0; while (cond) { __builtin_amdgcn_s_sleep(1); \
;     if ((++_sp & 255u) == 0u) { if (xb_ld(&(bar)[XB_TMO])) break; if (_sp > XB_SPIN_CAP) { atomicAdd(&(bar)[XB_TMO], 1u); break; } } } } while (0)
; __device__ __forceinline__ void xcd_barrier(const XcdBarrier& b) {
;     ...
;             __builtin_amdgcn_fence(__ATOMIC_ACQUIRE, "agent");
;             xb_add(&bar[XB_XGEN(b.x)], 1u);
;             asm volatile("s_waitcnt vmcnt(0)" ::: "memory");
;         } else {
;             XB_SPIN(xb_ld(&bar[XB_XGEN(b.x)]) == gen, bar);
;             __builtin_amdgcn_fence(__ATOMIC_ACQUIRE, "agent");
;             asm volatile("s_waitcnt vmcnt(0)" ::: "memory");
.LBB0_1016:
	s_or_b64 exec, exec, s[8:9]
	s_mov_b64 s[8:9], exec
	v_mbcnt_lo_u32_b32 v0, s8, 0
	v_mbcnt_hi_u32_b32 v0, s9, v0
	v_cmp_eq_u32_e32 vcc, 0, v0
	s_waitcnt vmcnt(0)
	buffer_inv sc1
	s_and_saveexec_b64 s[10:11], vcc
	s_cbranch_execz .LBB0_1018
	s_bcnt1_i32_b64 s8, s[8:9]
	v_mov_b32_e32 v0, s8
.LBB0_1018:
	s_or_b64 exec, exec, s[10:11]
	s_waitcnt vmcnt(0)

; __device__ __forceinline__ unsigned xb_ld(unsigned* p)              { return __hip_atomic_load(p, __ATOMIC_RELAXED, __HIP_MEMORY_SCOPE_AGENT); }
; __device__ __forceinline__ unsigned xb_add(unsigned* p, unsigned v) { return __hip_atomic_fetch_add(p, v, __ATOMIC_RELAXED, __HIP_MEMORY_SCOPE_AGENT); }
; #define XB_SPIN(cond, bar) do { unsigned _sp = 0; while (cond) { __builtin_amdgcn_s_sleep(1); \
;     if ((++_sp & 255u) == 0u) { if (xb_ld(&(bar)[XB_TMO])) break; if (_sp > XB_SPIN_CAP) { atomicAdd(&(bar)[XB_TMO], 1u); break; } } } } while (0)
; __device__ __forceinline__ void xcd_barrier(const XcdBarrier& b) {
;     ...
;             const unsigned og = xb_add(&bar[XB_TOP], 1u);
;             const unsigned tg = og / nx;
;             if (og + 1u == (tg + 1u) * nx) xb_add(&bar[XB_TOPGEN], 1u);
;             else XB_SPIN(xb_ld(&bar[XB_TOPGEN]) == tg, bar);
;             __builtin_amdgcn_fence(__ATOMIC_ACQUIRE, "agent");
;             xb_add(&bar[XB_XGEN(b.x)], 1u);
;             asm volatile("s_waitcnt vmcnt(0)" ::: "memory");
;         } else {
;             XB_SPIN(xb_ld(&bar[XB_XGEN(b.x)]) == gen, bar);
;             __builtin_amdgcn_fence(__ATOMIC_ACQUIRE, "agent");
;             asm volatile("s_waitcnt vmcnt(0)" ::: "memory");
.LBB0_1118:
	s_or_b64 exec, exec, s[8:9]
	s_and_saveexec_b64 s[8:9], s[12:13]
	s_cbranch_execz .LBB0_1120
	global_atomic_add v[0:1], v156, off
	v_readlane_b32 vcc_lo, v253, 63
	v_readlane_b32 vcc_hi, v254, 0
	s_nop 4
	global_atomic_add v97, v156, vcc offset:-4096
	global_atomic_add v97, v156, vcc offset:-3840
	global_atomic_add v97, v156, vcc offset:-3584
	global_atomic_add v97, v156, vcc offset:-3328
	global_atomic_add v97, v156, vcc offset:-3072
	global_atomic_add v97, v156, vcc offset:-2816
	global_atomic_add v97, v156, vcc offset:-2560
	global_atomic_add v97, v156, vcc offset:-2304
.LBB0_1120:
	s_or_b64 exec, exec, s[8:9]
	s_mov_b64 s[8:9], exec
	v_mbcnt_lo_u32_b32 v0, s8, 0
	v_mbcnt_hi_u32_b32 v0, s9, v0
	v_cmp_eq_u32_e32 vcc, 0, v0
	s_waitcnt vmcnt(0)
	buffer_inv sc1
	s_and_saveexec_b64 s[12:13], vcc
	s_cbranch_execz .LBB0_1122
	s_bcnt1_i32_b64 s8, s[8:9]
	v_mov_b32_e32 v0, s8
.LBB0_1122:
	s_or_b64 exec, exec, s[12:13]
	s_waitcnt vmcnt(0)

; __device__ __forceinline__ unsigned xb_ld(unsigned* p)              { return __hip_atomic_load(p, __ATOMIC_RELAXED, __HIP_MEMORY_SCOPE_AGENT); }
; __device__ __forceinline__ unsigned xb_add(unsigned* p, unsigned v) { return __hip_atomic_fetch_add(p, v, __ATOMIC_RELAXED, __HIP_MEMORY_SCOPE_AGENT); }
; #define XB_SPIN(cond, bar) do { unsigned _sp = 0; while (cond) { __builtin_amdgcn_s_sleep(1); \
;     if ((++_sp & 255u) == 0u) { if (xb_ld(&(bar)[XB_TMO])) break; if (_sp > XB_SPIN_CAP) { atomicAdd(&(bar)[XB_TMO], 1u); break; } } } } while (0)
; #define GSYNC() do { XcdBarrier b_; b_.bar = (unsigned*)(p.ws + OFF_BAR); b_.x = xb_xcc_id(); b_.st = (volatile LAS unsigned*)(lds + 131072); xcd_barrier(b_); } while (0)
; __device__ __forceinline__ void xcd_barrier(const XcdBarrier& b) {
;     ...
;             __builtin_amdgcn_fence(__ATOMIC_ACQUIRE, "agent");
;             xb_add(&bar[XB_XGEN(b.x)], 1u);
;             asm volatile("s_waitcnt vmcnt(0)" ::: "memory");
;         } else {
;             XB_SPIN(xb_ld(&bar[XB_XGEN(b.x)]) == gen, bar);
;             __builtin_amdgcn_fence(__ATOMIC_ACQUIRE, "agent");
;             asm volatile("s_waitcnt vmcnt(0)" ::: "memory");
; __global__ void __launch_bounds__(NTHREADS, 2) mega_fwd(Params p) {
;     ...
;         GSYNC();
.LBB0_1195:
	s_or_b64 exec, exec, s[6:7]
	s_mov_b64 s[6:7], exec
	v_mbcnt_lo_u32_b32 v0, s6, 0
	v_mbcnt_hi_u32_b32 v0, s7, v0
	v_cmp_eq_u32_e32 vcc, 0, v0
	s_waitcnt vmcnt(0)
	buffer_inv sc1
	s_and_saveexec_b64 s[8:9], vcc
	s_cbranch_execz .LBB0_181
	s_bcnt1_i32_b64 s6, s[6:7]
	v_mov_b32_e32 v0, s6
	s_branch .LBB0_181
